# v50 = v49 + prep_kv k_rope: the eight per-thread element loads issued together (one memory round trip instead of up to eight)
# baseline (speedup 1.0000x reference)
.LBB0_376:
	s_sub_u32 s0, s76, 0x400
	s_cmp_lt_u32 s0, 0x200
	s_sub_i32 s0, 0x9ff, s76
	s_cselect_b32 s76, s0, s76
	s_mul_hi_i32 s0, s76, 0x38e38e39
	s_lshr_b32 s1, s0, 31
	s_ashr_i32 s0, s0, 8
	s_add_i32 s0, s0, s1
	s_mulk_i32 s0, 0x480
	s_sub_i32 s26, s76, s0
	s_add_i32 s0, s76, 0x47f
	s_lshl_b32 s18, s26, 5
	s_cmpk_gt_u32 s0, 0x8fe
	s_mov_b64 s[0:1], -1
	s_cbranch_scc0 .LBB0_421
	s_add_i32 s0, s76, 0xfffffb80
	s_cmpk_gt_u32 s0, 0x47f
	s_mov_b64 s[0:1], -1
	s_cbranch_scc0 .LBB0_387
	s_mov_b64 s[8:9], s[30:31]
	v_mov_b32_e32 v0, v65
	s_sext_i32_i16 s4, s26
	v_mbcnt_lo_u32_b32 v0, -1, v0
	v_mbcnt_hi_u32_b32 v0, -1, v0
	v_add_u32_e32 v79, s33, v0
	v_mov_b32_e32 v0, s8
	v_mov_b32_e32 v1, s9
	v_add_co_u32_e32 v0, vcc, s55, v0
	s_mulk_i32 s4, 0xe39
	s_nop 0
	v_addc_co_u32_e32 v1, vcc, 0, v1, vcc
	global_load_dwordx2 v[0:1], v[0:1], off offset:504
	s_lshr_b32 s5, s4, 31
	s_ashr_i32 s13, s4, 18
	s_add_i32 s13, s13, s5
	s_add_u32 s10, s8, 0x7157900
	s_addc_u32 s11, s9, 0
	v_ashrrev_i32_e32 v36, 3, v79
	v_lshlrev_b32_e32 v78, 4, v79
	v_mov_b64_e32 v[12:13], s[10:11]
	v_add_u32_e32 v2, s18, v36
	v_and_b32_e32 v14, 0x70, v78
	v_mad_i64_i32 v[2:3], s[4:5], v2, s34, v[12:13]
	v_lshlrev_b32_e32 v64, 1, v14
	s_mov_b64 s[0:1], 0x1100
	v_lshl_add_u64 v[2:3], v[2:3], 0, v[64:65]
	v_lshl_add_u64 v[4:5], v[2:3], 0, s[0:1]
	v_add_co_u32_e32 v2, vcc, s35, v2
	global_load_dwordx4 v[8:11], v[4:5], off offset:16
	s_nop 0
	v_addc_co_u32_e32 v3, vcc, 0, v3, vcc
	global_load_dwordx4 v[4:7], v[2:3], off offset:256
	v_mov_b32_e32 v3, v65
	v_lshlrev_b32_e32 v2, 2, v14
	s_waitcnt lgkmcnt(0)
	s_barrier
	v_ashrrev_i32_e32 v81, 5, v79
	v_add_u32_e32 v66, s18, v81
	v_and_b32_e32 v80, 31, v79
	v_cmp_gt_u32_e64 s[6:7], 16, v80
	s_waitcnt vmcnt(0)
	v_readfirstlane_b32 s1, v1
	v_readfirstlane_b32 s0, v0
	v_lshlrev_b32_e32 v15, 16, v9
	s_nop 0
	v_lshl_add_u64 v[18:19], s[0:1], 0, v[2:3]
	global_load_dwordx4 v[0:3], v[18:19], off
	global_load_dwordx4 v[20:23], v[18:19], off offset:16
	v_and_b32_e32 v27, 0xffff0000, v5
	v_and_b32_e32 v26, 0xffff0000, v4
	v_lshlrev_b32_e32 v25, 16, v5
	v_lshlrev_b32_e32 v24, 16, v4
	v_and_b32_e32 v31, 0xffff0000, v7
	v_and_b32_e32 v30, 0xffff0000, v6
	v_pk_mul_f32 v[32:33], v[26:27], v[26:27]
	v_lshlrev_b32_e32 v29, 16, v7
	v_lshlrev_b32_e32 v28, 16, v6
	v_pk_mul_f32 v[34:35], v[30:31], v[30:31]
	v_pk_fma_f32 v[32:33], v[24:25], v[24:25], v[32:33]
	v_lshlrev_b32_e32 v14, 16, v8
	v_and_b32_e32 v9, 0xffff0000, v9
	v_and_b32_e32 v8, 0xffff0000, v8
	v_pk_fma_f32 v[34:35], v[28:29], v[28:29], v[34:35]
	v_add_f32_e32 v32, v32, v33
	v_pk_mul_f32 v[4:5], v[8:9], v[8:9]
	v_add_f32_e32 v32, v34, v32
	v_lshlrev_b32_e32 v17, 16, v11
	v_lshlrev_b32_e32 v16, 16, v10
	v_and_b32_e32 v11, 0xffff0000, v11
	v_and_b32_e32 v10, 0xffff0000, v10
	v_pk_fma_f32 v[4:5], v[14:15], v[14:15], v[4:5]
	v_add_f32_e32 v32, v35, v32
	v_pk_mul_f32 v[6:7], v[10:11], v[10:11]
	v_add_f32_e32 v4, v4, v32
	v_pk_fma_f32 v[6:7], v[16:17], v[16:17], v[6:7]
	v_add_f32_e32 v4, v5, v4
	v_add_f32_e32 v4, v6, v4
	v_add_f32_e32 v4, v7, v4
	s_waitcnt vmcnt(0) lgkmcnt(0)
	v_mov_b32_e32 v32, v0
	v_add_f32_dpp v4, v4, v4 quad_perm:[1,0,3,2] row_mask:0xf bank_mask:0xf bound_ctrl:1
	v_mov_b32_e32 v33, v2
	v_mov_b32_e32 v2, v1
	v_add_f32_dpp v4, v4, v4 quad_perm:[2,3,0,1] row_mask:0xf bank_mask:0xf bound_ctrl:1
	v_mov_b32_e32 v0, v20
	v_mov_b32_e32 v1, v22
	v_add_f32_dpp v4, v4, v4 row_half_mirror row_mask:0xf bank_mask:0xf bound_ctrl:1
	v_fmamk_f32 v4, v4, 0x3c000000, v127
	v_mul_f32_e32 v5, 0x4b800000, v4
	v_cmp_gt_f32_e32 vcc, s57, v4
	v_mov_b32_e32 v22, v21
	s_nop 0
	v_cndmask_b32_e32 v4, v4, v5, vcc
	v_rsq_f32_e32 v6, v4
	v_mad_u64_u32 v[4:5], s[0:1], v36, s56, v[64:65]
	v_lshlrev_b32_e32 v64, 1, v80
	v_mul_f32_e32 v5, 0x45800000, v6
	v_cndmask_b32_e32 v6, v6, v5, vcc
	v_pk_mul_f32 v[24:25], v[6:7], v[24:25] op_sel_hi:[0,1]
	v_pk_mul_f32 v[26:27], v[6:7], v[26:27] op_sel_hi:[0,1]
	v_pk_mul_f32 v[28:29], v[6:7], v[28:29] op_sel_hi:[0,1]
	v_pk_mul_f32 v[30:31], v[6:7], v[30:31] op_sel_hi:[0,1]
	v_pk_mul_f32 v[20:21], v[32:33], v[24:25]
	v_pk_mul_f32 v[2:3], v[2:3], v[26:27]
	v_pk_mul_f32 v[0:1], v[0:1], v[28:29]
	v_pk_mul_f32 v[22:23], v[22:23], v[30:31]
	v_bfe_u32 v24, v3, 16, 1
	v_bfe_u32 v5, v23, 16, 1
	v_bfe_u32 v7, v22, 16, 1
	v_bfe_u32 v25, v2, 16, 1
	v_bfe_u32 v26, v20, 16, 1
	v_bfe_u32 v27, v21, 16, 1
	v_bfe_u32 v28, v0, 16, 1
	v_bfe_u32 v29, v1, 16, 1
	v_add3_u32 v25, v2, v25, s58
	v_add3_u32 v24, v3, v24, s58
	v_add3_u32 v2, v22, v7, s58
	v_add3_u32 v3, v23, v5, s58
	v_add3_u32 v1, v1, v29, s58
	v_add3_u32 v0, v0, v28, s58
	v_add3_u32 v5, v21, v27, s58
	v_add3_u32 v7, v20, v26, s58
	v_lshrrev_b32_e32 v7, 16, v7
	v_lshrrev_b32_e32 v5, 16, v5
	v_lshrrev_b32_e32 v0, 16, v0
	v_lshrrev_b32_e32 v1, 16, v1
	v_and_or_b32 v3, v3, s54, v1
	v_and_or_b32 v2, v2, s54, v0
	v_and_or_b32 v1, v24, s54, v5
	v_and_or_b32 v0, v25, s54, v7
	ds_write_b128 v4, v[0:3]
	global_load_dwordx4 v[20:23], v[18:19], off offset:32
	global_load_dwordx4 v[24:27], v[18:19], off offset:48
	v_mad_i64_i32 v[0:1], s[0:1], v66, s34, v[12:13]
	v_pk_mul_f32 v[12:13], v[6:7], v[14:15] op_sel_hi:[0,1]
	v_pk_mul_f32 v[8:9], v[6:7], v[8:9] op_sel_hi:[0,1]
	v_pk_mul_f32 v[14:15], v[6:7], v[16:17] op_sel_hi:[0,1]
	v_pk_mul_f32 v[6:7], v[6:7], v[10:11] op_sel_hi:[0,1]
	v_lshl_add_u64 v[0:1], v[0:1], 0, s[20:21]
	v_lshl_add_u64 v[2:3], v[0:1], 0, v[64:65]
	s_mul_i32 s0, s13, 0xfffff700
	s_add_i32 s12, s0, s18
	s_cmpk_gt_i32 s12, 0xff
	s_cselect_b64 s[24:25], -1, 0
	s_cmpk_lt_i32 s12, 0x100
	s_waitcnt vmcnt(0) lgkmcnt(0)
	v_mov_b32_e32 v10, v20
	v_mov_b32_e32 v11, v22
	v_mov_b32_e32 v22, v21
	v_mov_b32_e32 v16, v24
	v_mov_b32_e32 v17, v26
	v_mov_b32_e32 v26, v25
	v_pk_mul_f32 v[10:11], v[10:11], v[12:13]
	v_pk_mul_f32 v[8:9], v[22:23], v[8:9]
	v_pk_mul_f32 v[12:13], v[16:17], v[14:15]
	v_pk_mul_f32 v[6:7], v[6:7], v[26:27]
	v_bfe_u32 v15, v9, 16, 1
	v_bfe_u32 v5, v7, 16, 1
	v_bfe_u32 v16, v8, 16, 1
	v_bfe_u32 v17, v10, 16, 1
	v_bfe_u32 v18, v11, 16, 1
	v_bfe_u32 v19, v12, 16, 1
	v_bfe_u32 v20, v13, 16, 1
	v_bfe_u32 v14, v6, 16, 1
	v_add3_u32 v16, v8, v16, s58
	v_add3_u32 v15, v9, v15, s58
	v_add3_u32 v5, v7, v5, s58
	v_add3_u32 v7, v13, v20, s58
	v_add3_u32 v8, v12, v19, s58
	v_add3_u32 v9, v11, v18, s58
	v_add3_u32 v10, v10, v17, s58
	v_add3_u32 v6, v6, v14, s58
	v_lshrrev_b32_e32 v10, 16, v10
	v_lshrrev_b32_e32 v11, 16, v9
	v_lshrrev_b32_e32 v8, 16, v8
	v_lshrrev_b32_e32 v7, 16, v7
	v_and_or_b32 v9, v5, s54, v7
	v_and_or_b32 v8, v6, s54, v8
	v_and_or_b32 v7, v15, s54, v11
	v_and_or_b32 v6, v16, s54, v10
	ds_write_b128 v4, v[6:9] offset:16
	global_load_ushort v2, v[2:3], off
	v_mov_b32_e32 v245, 0
	v_xor_b32_e32 v244, 16, v64
	v_lshl_add_u64 v[242:243], v[0:1], 0, v[244:245]
	global_load_ushort v235, v[242:243], off
	v_add_u32_e32 v244, 0x9200, v64
	v_lshl_add_u64 v[242:243], v[0:1], 0, v[244:245]
	global_load_ushort v232, v[242:243], off
	v_xor_b32_e32 v244, 16, v244
	v_lshl_add_u64 v[242:243], v[0:1], 0, v[244:245]
	global_load_ushort v236, v[242:243], off
	v_add_u32_e32 v244, 0x12400, v64
	v_lshl_add_u64 v[242:243], v[0:1], 0, v[244:245]
	global_load_ushort v233, v[242:243], off
	v_xor_b32_e32 v244, 16, v244
	v_lshl_add_u64 v[242:243], v[0:1], 0, v[244:245]
	global_load_ushort v237, v[242:243], off
	v_add_u32_e32 v244, 0x1b600, v64
	v_lshl_add_u64 v[242:243], v[0:1], 0, v[244:245]
	global_load_ushort v234, v[242:243], off
	v_xor_b32_e32 v244, 16, v244
	v_lshl_add_u64 v[242:243], v[0:1], 0, v[244:245]
	global_load_ushort v238, v[242:243], off
	v_and_b32_e32 v4, 7, v79
	v_cvt_f32_ubyte0_e32 v4, v4
	v_mul_f32_e32 v6, 0xbfd49a78, v4
	v_cmp_gt_f32_e32 vcc, s59, v6
	v_and_b32_e32 v5, 8, v79
	v_bitop3_b32 v3, v79, 8, 31 bitop3:0x6c
	v_cndmask_b32_e32 v6, 0, v129, vcc
	v_fmac_f32_e32 v6, 0xbfd49a78, v4
	v_exp_f32_e32 v4, v6
	v_cmp_eq_u32_e64 s[4:5], 0, v5
	v_cndmask_b32_e32 v5, 0, v130, vcc
	v_ldexp_f32 v6, v4, v5
	s_waitcnt vmcnt(0) lgkmcnt(0)
	v_lshlrev_b32_e32 v4, 16, v2
	v_lshlrev_b32_e32 v2, 1, v3
	s_cbranch_scc1 .LBB0_380
	v_mov_b32_e32 v3, v65
	v_lshl_add_u64 v[0:1], v[0:1], 0, v[2:3]
	v_mov_b32_e32 v0, v235
	v_add_u32_e32 v1, s12, v81
	v_add_u32_e32 v3, 0xffffff00, v1
	v_ashrrev_i32_e32 v3, 6, v3
	v_and_b32_e32 v1, 63, v1
	v_cndmask_b32_e64 v1, v1, v3, s[6:7]
	v_cvt_f32_i32_e32 v1, v1
	v_mul_f32_e32 v1, v6, v1
	v_mul_f32_e32 v1, 0.15915494, v1
	v_sin_f32_e32 v3, v1
	v_cos_f32_e32 v1, v1
	s_waitcnt vmcnt(0) lgkmcnt(0)
	v_lshlrev_b32_e32 v0, 16, v0
	v_mul_f32_e32 v0, v3, v0
	v_cndmask_b32_e64 v0, v0, -v0, s[4:5]
	v_fmac_f32_e32 v0, v1, v4
	v_mov_b32_e32 v4, v0
.LBB0_380:
	v_ashrrev_i32_e32 v67, 31, v66
	v_lshl_add_u64 v[0:1], s[8:9], 0, v[64:65]
	s_mov_b64 s[0:1], 0x14297900
	v_bfe_u32 v3, v4, 16, 1
	v_lshl_add_u64 v[0:1], v[0:1], 0, s[0:1]
	v_add3_u32 v3, v4, v3, s58
	v_lshlrev_b64 v[4:5], 6, v[66:67]
	v_lshl_add_u64 v[4:5], v[0:1], 0, v[4:5]
	global_store_short_d16_hi v[4:5], v3, off
	v_add_u32_e32 v3, 0x100, v79
	v_ashrrev_i32_e32 v82, 5, v3
	v_add_u32_e32 v68, s18, v82
	v_mov_b64_e32 v[4:5], s[10:11]
	v_mad_i64_i32 v[4:5], s[0:1], v68, s34, v[4:5]
	v_lshl_add_u64 v[4:5], v[4:5], 0, s[20:21]
	v_lshl_add_u64 v[8:9], v[4:5], 0, v[64:65]
	v_mov_b32_e32 v3, v232
	v_cndmask_b32_e64 v7, 0, 1, s[24:25]
	v_cmp_ne_u32_e64 s[0:1], 1, v7
	s_andn2_b64 vcc, exec, s[24:25]
	s_waitcnt vmcnt(0) lgkmcnt(0)
	v_lshlrev_b32_e32 v7, 16, v3
	s_cbranch_vccnz .LBB0_382
	v_mov_b32_e32 v3, v65
	v_lshl_add_u64 v[4:5], v[4:5], 0, v[2:3]
	v_mov_b32_e32 v3, v236
	v_add_u32_e32 v4, s12, v82
	v_add_u32_e32 v5, 0xffffff00, v4
	v_ashrrev_i32_e32 v5, 6, v5
	v_and_b32_e32 v4, 63, v4
	v_cndmask_b32_e64 v4, v4, v5, s[6:7]
	v_cvt_f32_i32_e32 v4, v4
	v_mul_f32_e32 v4, v6, v4
	v_mul_f32_e32 v4, 0.15915494, v4
	v_sin_f32_e32 v5, v4
	v_cos_f32_e32 v4, v4
	s_waitcnt vmcnt(0) lgkmcnt(0)
	v_lshlrev_b32_e32 v3, 16, v3
	v_mul_f32_e32 v3, v5, v3
	v_cndmask_b32_e64 v3, v3, -v3, s[4:5]
	v_fmac_f32_e32 v3, v4, v7
	v_mov_b32_e32 v7, v3
.LBB0_382:
	v_ashrrev_i32_e32 v69, 31, v68
	v_bfe_u32 v3, v7, 16, 1
	v_lshlrev_b64 v[4:5], 6, v[68:69]
	v_add3_u32 v3, v7, v3, s58
	v_lshl_add_u64 v[4:5], v[0:1], 0, v[4:5]
	global_store_short_d16_hi v[4:5], v3, off
	v_add_u32_e32 v3, 0x200, v79
	v_ashrrev_i32_e32 v83, 5, v3
	v_add_u32_e32 v70, s18, v83
	v_mov_b64_e32 v[4:5], s[10:11]
	v_mad_i64_i32 v[4:5], s[24:25], v70, s34, v[4:5]
	v_lshl_add_u64 v[4:5], v[4:5], 0, s[20:21]
	v_lshl_add_u64 v[8:9], v[4:5], 0, v[64:65]
	v_mov_b32_e32 v3, v233
	s_and_b64 vcc, exec, s[0:1]
	s_waitcnt vmcnt(0) lgkmcnt(0)
	v_lshlrev_b32_e32 v7, 16, v3
	s_cbranch_vccnz .LBB0_384
	v_mov_b32_e32 v3, v65
	v_lshl_add_u64 v[4:5], v[4:5], 0, v[2:3]
	v_mov_b32_e32 v3, v237
	v_add_u32_e32 v4, s12, v83
	v_add_u32_e32 v5, 0xffffff00, v4
	v_ashrrev_i32_e32 v5, 6, v5
	v_and_b32_e32 v4, 63, v4
	v_cndmask_b32_e64 v4, v4, v5, s[6:7]
	v_cvt_f32_i32_e32 v4, v4
	v_mul_f32_e32 v4, v6, v4
	v_mul_f32_e32 v4, 0.15915494, v4
	v_sin_f32_e32 v5, v4
	v_cos_f32_e32 v4, v4
	s_waitcnt vmcnt(0) lgkmcnt(0)
	v_lshlrev_b32_e32 v3, 16, v3
	v_mul_f32_e32 v3, v5, v3
	v_cndmask_b32_e64 v3, v3, -v3, s[4:5]
	v_fmac_f32_e32 v3, v4, v7
	v_mov_b32_e32 v7, v3
.LBB0_384:
	v_ashrrev_i32_e32 v71, 31, v70
	v_bfe_u32 v3, v7, 16, 1
	v_lshlrev_b64 v[4:5], 6, v[70:71]
	v_add3_u32 v3, v7, v3, s58
	v_lshl_add_u64 v[4:5], v[0:1], 0, v[4:5]
	global_store_short_d16_hi v[4:5], v3, off
	v_add_u32_e32 v3, 0x300, v79
	v_ashrrev_i32_e32 v84, 5, v3
	v_add_u32_e32 v72, s18, v84
	v_mov_b64_e32 v[4:5], s[10:11]
	v_mad_i64_i32 v[4:5], s[10:11], v72, s34, v[4:5]
	v_lshl_add_u64 v[4:5], v[4:5], 0, s[20:21]
	v_lshl_add_u64 v[8:9], v[4:5], 0, v[64:65]
	v_mov_b32_e32 v3, v234
	s_and_b64 vcc, exec, s[0:1]
	s_waitcnt vmcnt(0) lgkmcnt(0)
	v_lshlrev_b32_e32 v7, 16, v3
	s_cbranch_vccnz .LBB0_386
	v_mov_b32_e32 v3, v65
	v_lshl_add_u64 v[2:3], v[4:5], 0, v[2:3]
	v_mov_b32_e32 v2, v238
	v_add_u32_e32 v3, s12, v84
	v_add_u32_e32 v4, 0xffffff00, v3
	v_ashrrev_i32_e32 v4, 6, v4
	v_and_b32_e32 v3, 63, v3
	v_cndmask_b32_e64 v3, v3, v4, s[6:7]
	v_cvt_f32_i32_e32 v3, v3
	v_mul_f32_e32 v3, v6, v3
	v_mul_f32_e32 v3, 0.15915494, v3
	v_sin_f32_e32 v4, v3
	v_cos_f32_e32 v3, v3
	s_waitcnt vmcnt(0) lgkmcnt(0)
	v_lshlrev_b32_e32 v2, 16, v2
	v_mul_f32_e32 v2, v4, v2
	v_cndmask_b32_e64 v2, v2, -v2, s[4:5]
	v_fmac_f32_e32 v2, v3, v7
	v_mov_b32_e32 v7, v2

.LBB0_1358:
	s_sub_u32 s0, s78, 0x400
	s_cmp_lt_u32 s0, 0x200
	s_sub_i32 s0, 0x9ff, s78
	s_cselect_b32 s78, s0, s78
	s_mul_hi_i32 s0, s78, 0x38e38e39
	s_lshr_b32 s1, s0, 31
	s_ashr_i32 s0, s0, 8
	s_add_i32 s0, s0, s1
	s_mulk_i32 s0, 0x480
	s_sub_i32 s26, s78, s0
	s_sext_i32_i16 s0, s26
	s_mulk_i32 s0, 0xe39
	s_lshr_b32 s1, s0, 31
	s_ashr_i32 s18, s0, 18
	s_add_i32 s18, s18, s1
	s_mul_i32 s0, s18, 0x48
	s_sub_i32 s0, s26, s0
	s_sext_i32_i16 s0, s0
	s_cmp_lt_i32 s0, 8
	s_cselect_b64 s[4:5], -1, 0
	s_add_i32 s6, s78, 0xfffffb80
	s_cmpk_gt_u32 s6, 0x47f
	s_cselect_b64 s[0:1], -1, 0
	s_cmpk_lt_u32 s6, 0x480
	s_cselect_b64 s[6:7], -1, 0
	s_and_b64 s[4:5], s[6:7], s[4:5]
	s_and_b64 vcc, exec, s[4:5]
	s_cbranch_vccnz .LBB0_1357
	s_add_i32 s4, s78, 0x47f
	s_cmpk_gt_u32 s4, 0x8fe
	s_mov_b64 s[4:5], -1
	s_cbranch_scc0 .LBB0_1404
	s_lshl_b32 s27, s26, 5
	s_and_b64 vcc, exec, s[0:1]
	s_cbranch_vccz .LBB0_1370
	s_mov_b64 s[8:9], s[30:31]
	v_mov_b32_e32 v0, v65
	s_add_u32 s10, s8, 0x7157900
	v_mbcnt_lo_u32_b32 v0, -1, v0
	v_mbcnt_hi_u32_b32 v0, -1, v0
	v_add_u32_e32 v79, s33, v0
	v_mov_b32_e32 v0, s8
	v_mov_b32_e32 v1, s9
	v_add_co_u32_e32 v0, vcc, s57, v0
	s_addc_u32 s11, s9, 0
	s_nop 0
	v_addc_co_u32_e32 v1, vcc, 0, v1, vcc
	global_load_dwordx2 v[0:1], v[0:1], off offset:504
	v_ashrrev_i32_e32 v36, 3, v79
	v_lshlrev_b32_e32 v78, 4, v79
	v_mov_b64_e32 v[12:13], s[10:11]
	v_add_u32_e32 v2, s27, v36
	v_and_b32_e32 v14, 0x70, v78
	v_mad_i64_i32 v[2:3], s[4:5], v2, s34, v[12:13]
	v_lshlrev_b32_e32 v64, 1, v14
	s_mov_b64 s[0:1], 0x1100
	v_lshl_add_u64 v[2:3], v[2:3], 0, v[64:65]
	v_lshl_add_u64 v[4:5], v[2:3], 0, s[0:1]
	v_add_co_u32_e32 v2, vcc, s35, v2
	global_load_dwordx4 v[8:11], v[4:5], off offset:16
	s_nop 0
	v_addc_co_u32_e32 v3, vcc, 0, v3, vcc
	global_load_dwordx4 v[4:7], v[2:3], off offset:256
	v_mov_b32_e32 v3, v65
	v_lshlrev_b32_e32 v2, 2, v14
	s_waitcnt lgkmcnt(0)
	s_barrier
	v_ashrrev_i32_e32 v81, 5, v79
	v_add_u32_e32 v66, s27, v81
	v_and_b32_e32 v80, 31, v79
	s_sext_i32_i16 s13, s18
	v_cmp_gt_u32_e64 s[6:7], 16, v80
	s_waitcnt vmcnt(0)
	v_readfirstlane_b32 s1, v1
	v_readfirstlane_b32 s0, v0
	v_lshlrev_b32_e32 v15, 16, v9
	s_nop 0
	v_lshl_add_u64 v[18:19], s[0:1], 0, v[2:3]
	global_load_dwordx4 v[0:3], v[18:19], off offset:512
	global_load_dwordx4 v[20:23], v[18:19], off offset:528
	v_and_b32_e32 v27, 0xffff0000, v5
	v_and_b32_e32 v26, 0xffff0000, v4
	v_lshlrev_b32_e32 v25, 16, v5
	v_lshlrev_b32_e32 v24, 16, v4
	v_and_b32_e32 v31, 0xffff0000, v7
	v_and_b32_e32 v30, 0xffff0000, v6
	v_pk_mul_f32 v[32:33], v[26:27], v[26:27]
	v_lshlrev_b32_e32 v29, 16, v7
	v_lshlrev_b32_e32 v28, 16, v6
	v_pk_mul_f32 v[34:35], v[30:31], v[30:31]
	v_pk_fma_f32 v[32:33], v[24:25], v[24:25], v[32:33]
	v_lshlrev_b32_e32 v14, 16, v8
	v_and_b32_e32 v9, 0xffff0000, v9
	v_and_b32_e32 v8, 0xffff0000, v8
	v_pk_fma_f32 v[34:35], v[28:29], v[28:29], v[34:35]
	v_add_f32_e32 v32, v32, v33
	v_pk_mul_f32 v[4:5], v[8:9], v[8:9]
	v_add_f32_e32 v32, v34, v32
	v_lshlrev_b32_e32 v17, 16, v11
	v_lshlrev_b32_e32 v16, 16, v10
	v_and_b32_e32 v11, 0xffff0000, v11
	v_and_b32_e32 v10, 0xffff0000, v10
	v_pk_fma_f32 v[4:5], v[14:15], v[14:15], v[4:5]
	v_add_f32_e32 v32, v35, v32
	v_pk_mul_f32 v[6:7], v[10:11], v[10:11]
	v_add_f32_e32 v4, v4, v32
	v_pk_fma_f32 v[6:7], v[16:17], v[16:17], v[6:7]
	v_add_f32_e32 v4, v5, v4
	v_add_f32_e32 v4, v6, v4
	v_add_f32_e32 v4, v7, v4
	s_waitcnt vmcnt(0) lgkmcnt(0)
	v_mov_b32_e32 v32, v0
	v_add_f32_dpp v4, v4, v4 quad_perm:[1,0,3,2] row_mask:0xf bank_mask:0xf bound_ctrl:1
	v_mov_b32_e32 v33, v2
	v_mov_b32_e32 v2, v1
	v_add_f32_dpp v4, v4, v4 quad_perm:[2,3,0,1] row_mask:0xf bank_mask:0xf bound_ctrl:1
	v_mov_b32_e32 v0, v20
	v_mov_b32_e32 v1, v22
	v_add_f32_dpp v4, v4, v4 row_half_mirror row_mask:0xf bank_mask:0xf bound_ctrl:1
	v_fmamk_f32 v4, v4, 0x3c000000, v127
	v_mul_f32_e32 v5, 0x4b800000, v4
	v_cmp_gt_f32_e32 vcc, s59, v4
	v_mov_b32_e32 v22, v21
	s_nop 0
	v_cndmask_b32_e32 v4, v4, v5, vcc
	v_rsq_f32_e32 v6, v4
	v_mad_u64_u32 v[4:5], s[0:1], v36, s58, v[64:65]
	v_lshlrev_b32_e32 v64, 1, v80
	v_mul_f32_e32 v5, 0x45800000, v6
	v_cndmask_b32_e32 v6, v6, v5, vcc
	v_pk_mul_f32 v[24:25], v[6:7], v[24:25] op_sel_hi:[0,1]
	v_pk_mul_f32 v[26:27], v[6:7], v[26:27] op_sel_hi:[0,1]
	v_pk_mul_f32 v[28:29], v[6:7], v[28:29] op_sel_hi:[0,1]
	v_pk_mul_f32 v[30:31], v[6:7], v[30:31] op_sel_hi:[0,1]
	v_pk_mul_f32 v[20:21], v[32:33], v[24:25]
	v_pk_mul_f32 v[2:3], v[2:3], v[26:27]
	v_pk_mul_f32 v[0:1], v[0:1], v[28:29]
	v_pk_mul_f32 v[22:23], v[22:23], v[30:31]
	v_bfe_u32 v24, v3, 16, 1
	v_bfe_u32 v5, v23, 16, 1
	v_bfe_u32 v7, v22, 16, 1
	v_bfe_u32 v25, v2, 16, 1
	v_bfe_u32 v26, v20, 16, 1
	v_bfe_u32 v27, v21, 16, 1
	v_bfe_u32 v28, v0, 16, 1
	v_bfe_u32 v29, v1, 16, 1
	v_add3_u32 v25, v2, v25, s60
	v_add3_u32 v24, v3, v24, s60
	v_add3_u32 v2, v22, v7, s60
	v_add3_u32 v3, v23, v5, s60
	v_add3_u32 v1, v1, v29, s60
	v_add3_u32 v0, v0, v28, s60
	v_add3_u32 v5, v21, v27, s60
	v_add3_u32 v7, v20, v26, s60
	v_lshrrev_b32_e32 v7, 16, v7
	v_lshrrev_b32_e32 v5, 16, v5
	v_lshrrev_b32_e32 v0, 16, v0
	v_lshrrev_b32_e32 v1, 16, v1
	v_and_or_b32 v3, v3, s56, v1
	v_and_or_b32 v2, v2, s56, v0
	v_and_or_b32 v1, v24, s56, v5
	v_and_or_b32 v0, v25, s56, v7
	ds_write_b128 v4, v[0:3]
	global_load_dwordx4 v[20:23], v[18:19], off offset:544
	global_load_dwordx4 v[24:27], v[18:19], off offset:560
	v_mad_i64_i32 v[0:1], s[0:1], v66, s34, v[12:13]
	v_pk_mul_f32 v[12:13], v[6:7], v[14:15] op_sel_hi:[0,1]
	v_pk_mul_f32 v[8:9], v[6:7], v[8:9] op_sel_hi:[0,1]
	v_pk_mul_f32 v[14:15], v[6:7], v[16:17] op_sel_hi:[0,1]
	v_pk_mul_f32 v[6:7], v[6:7], v[10:11] op_sel_hi:[0,1]
	v_lshl_add_u64 v[0:1], v[0:1], 0, s[20:21]
	v_lshl_add_u64 v[2:3], v[0:1], 0, v[64:65]
	s_mul_i32 s0, s13, 0xfffff700
	s_add_i32 s12, s0, s27
	s_cmpk_gt_i32 s12, 0xff
	s_cselect_b64 s[24:25], -1, 0
	s_cmpk_lt_i32 s12, 0x100
	s_waitcnt vmcnt(0) lgkmcnt(0)
	v_mov_b32_e32 v10, v20
	v_mov_b32_e32 v11, v22
	v_mov_b32_e32 v22, v21
	v_mov_b32_e32 v16, v24
	v_mov_b32_e32 v17, v26
	v_mov_b32_e32 v26, v25
	v_pk_mul_f32 v[10:11], v[10:11], v[12:13]
	v_pk_mul_f32 v[8:9], v[22:23], v[8:9]
	v_pk_mul_f32 v[12:13], v[16:17], v[14:15]
	v_pk_mul_f32 v[6:7], v[6:7], v[26:27]
	v_bfe_u32 v15, v9, 16, 1
	v_bfe_u32 v5, v7, 16, 1
	v_bfe_u32 v16, v8, 16, 1
	v_bfe_u32 v17, v10, 16, 1
	v_bfe_u32 v18, v11, 16, 1
	v_bfe_u32 v19, v12, 16, 1
	v_bfe_u32 v20, v13, 16, 1
	v_bfe_u32 v14, v6, 16, 1
	v_add3_u32 v16, v8, v16, s60
	v_add3_u32 v15, v9, v15, s60
	v_add3_u32 v5, v7, v5, s60
	v_add3_u32 v7, v13, v20, s60
	v_add3_u32 v8, v12, v19, s60
	v_add3_u32 v9, v11, v18, s60
	v_add3_u32 v10, v10, v17, s60
	v_add3_u32 v6, v6, v14, s60
	v_lshrrev_b32_e32 v10, 16, v10
	v_lshrrev_b32_e32 v11, 16, v9
	v_lshrrev_b32_e32 v8, 16, v8
	v_lshrrev_b32_e32 v7, 16, v7
	v_and_or_b32 v9, v5, s56, v7
	v_and_or_b32 v8, v6, s56, v8
	v_and_or_b32 v7, v15, s56, v11
	v_and_or_b32 v6, v16, s56, v10
	ds_write_b128 v4, v[6:9] offset:16
	global_load_ushort v2, v[2:3], off
	v_mov_b32_e32 v245, 0
	v_xor_b32_e32 v244, 16, v64
	v_lshl_add_u64 v[242:243], v[0:1], 0, v[244:245]
	global_load_ushort v235, v[242:243], off
	v_add_u32_e32 v244, 0x9200, v64
	v_lshl_add_u64 v[242:243], v[0:1], 0, v[244:245]
	global_load_ushort v232, v[242:243], off
	v_xor_b32_e32 v244, 16, v244
	v_lshl_add_u64 v[242:243], v[0:1], 0, v[244:245]
	global_load_ushort v236, v[242:243], off
	v_add_u32_e32 v244, 0x12400, v64
	v_lshl_add_u64 v[242:243], v[0:1], 0, v[244:245]
	global_load_ushort v233, v[242:243], off
	v_xor_b32_e32 v244, 16, v244
	v_lshl_add_u64 v[242:243], v[0:1], 0, v[244:245]
	global_load_ushort v237, v[242:243], off
	v_add_u32_e32 v244, 0x1b600, v64
	v_lshl_add_u64 v[242:243], v[0:1], 0, v[244:245]
	global_load_ushort v234, v[242:243], off
	v_xor_b32_e32 v244, 16, v244
	v_lshl_add_u64 v[242:243], v[0:1], 0, v[244:245]
	global_load_ushort v238, v[242:243], off
	v_and_b32_e32 v4, 7, v79
	v_cvt_f32_ubyte0_e32 v4, v4
	v_mul_f32_e32 v6, 0xbfd49a78, v4
	v_cmp_gt_f32_e32 vcc, s61, v6
	v_and_b32_e32 v5, 8, v79
	v_bitop3_b32 v3, v79, 8, 31 bitop3:0x6c
	v_cndmask_b32_e32 v6, 0, v129, vcc
	v_fmac_f32_e32 v6, 0xbfd49a78, v4
	v_exp_f32_e32 v4, v6
	v_cmp_eq_u32_e64 s[4:5], 0, v5
	v_cndmask_b32_e32 v5, 0, v130, vcc
	v_ldexp_f32 v6, v4, v5
	s_waitcnt vmcnt(0) lgkmcnt(0)
	v_lshlrev_b32_e32 v4, 16, v2
	v_lshlrev_b32_e32 v2, 1, v3
	s_cbranch_scc1 .LBB0_1363
	v_mov_b32_e32 v3, v65
	v_lshl_add_u64 v[0:1], v[0:1], 0, v[2:3]
	v_mov_b32_e32 v0, v235
	v_add_u32_e32 v1, s12, v81
	v_add_u32_e32 v3, 0xffffff00, v1
	v_ashrrev_i32_e32 v3, 6, v3
	v_and_b32_e32 v1, 63, v1
	v_cndmask_b32_e64 v1, v1, v3, s[6:7]
	v_cvt_f32_i32_e32 v1, v1
	v_mul_f32_e32 v1, v6, v1
	v_mul_f32_e32 v1, 0.15915494, v1
	v_sin_f32_e32 v3, v1
	v_cos_f32_e32 v1, v1
	s_waitcnt vmcnt(0) lgkmcnt(0)
	v_lshlrev_b32_e32 v0, 16, v0
	v_mul_f32_e32 v0, v3, v0
	v_cndmask_b32_e64 v0, v0, -v0, s[4:5]
	v_fmac_f32_e32 v0, v1, v4
	v_mov_b32_e32 v4, v0
.LBB0_1363:
	v_ashrrev_i32_e32 v67, 31, v66
	v_lshl_add_u64 v[0:1], s[8:9], 0, v[64:65]
	s_mov_b64 s[0:1], 0x14297900
	v_bfe_u32 v3, v4, 16, 1
	v_lshl_add_u64 v[0:1], v[0:1], 0, s[0:1]
	v_add3_u32 v3, v4, v3, s60
	v_lshlrev_b64 v[4:5], 6, v[66:67]
	v_lshl_add_u64 v[4:5], v[0:1], 0, v[4:5]
	global_store_short_d16_hi v[4:5], v3, off
	v_add_u32_e32 v3, 0x100, v79
	v_ashrrev_i32_e32 v82, 5, v3
	v_add_u32_e32 v68, s27, v82
	v_mov_b64_e32 v[4:5], s[10:11]
	v_mad_i64_i32 v[4:5], s[0:1], v68, s34, v[4:5]
	v_lshl_add_u64 v[4:5], v[4:5], 0, s[20:21]
	v_lshl_add_u64 v[8:9], v[4:5], 0, v[64:65]
	v_mov_b32_e32 v3, v232
	v_cndmask_b32_e64 v7, 0, 1, s[24:25]
	v_cmp_ne_u32_e64 s[0:1], 1, v7
	s_andn2_b64 vcc, exec, s[24:25]
	s_waitcnt vmcnt(0) lgkmcnt(0)
	v_lshlrev_b32_e32 v7, 16, v3
	s_cbranch_vccnz .LBB0_1365
	v_mov_b32_e32 v3, v65
	v_lshl_add_u64 v[4:5], v[4:5], 0, v[2:3]
	v_mov_b32_e32 v3, v236
	v_add_u32_e32 v4, s12, v82
	v_add_u32_e32 v5, 0xffffff00, v4
	v_ashrrev_i32_e32 v5, 6, v5
	v_and_b32_e32 v4, 63, v4
	v_cndmask_b32_e64 v4, v4, v5, s[6:7]
	v_cvt_f32_i32_e32 v4, v4
	v_mul_f32_e32 v4, v6, v4
	v_mul_f32_e32 v4, 0.15915494, v4
	v_sin_f32_e32 v5, v4
	v_cos_f32_e32 v4, v4
	s_waitcnt vmcnt(0) lgkmcnt(0)
	v_lshlrev_b32_e32 v3, 16, v3
	v_mul_f32_e32 v3, v5, v3
	v_cndmask_b32_e64 v3, v3, -v3, s[4:5]
	v_fmac_f32_e32 v3, v4, v7
	v_mov_b32_e32 v7, v3
.LBB0_1365:
	v_ashrrev_i32_e32 v69, 31, v68
	v_bfe_u32 v3, v7, 16, 1
	v_lshlrev_b64 v[4:5], 6, v[68:69]
	v_add3_u32 v3, v7, v3, s60
	v_lshl_add_u64 v[4:5], v[0:1], 0, v[4:5]
	global_store_short_d16_hi v[4:5], v3, off
	v_add_u32_e32 v3, 0x200, v79
	v_ashrrev_i32_e32 v83, 5, v3
	v_add_u32_e32 v70, s27, v83
	v_mov_b64_e32 v[4:5], s[10:11]
	v_mad_i64_i32 v[4:5], s[24:25], v70, s34, v[4:5]
	v_lshl_add_u64 v[4:5], v[4:5], 0, s[20:21]
	v_lshl_add_u64 v[8:9], v[4:5], 0, v[64:65]
	v_mov_b32_e32 v3, v233
	s_and_b64 vcc, exec, s[0:1]
	s_waitcnt vmcnt(0) lgkmcnt(0)
	v_lshlrev_b32_e32 v7, 16, v3
	s_cbranch_vccnz .LBB0_1367
	v_mov_b32_e32 v3, v65
	v_lshl_add_u64 v[4:5], v[4:5], 0, v[2:3]
	v_mov_b32_e32 v3, v237
	v_add_u32_e32 v4, s12, v83
	v_add_u32_e32 v5, 0xffffff00, v4
	v_ashrrev_i32_e32 v5, 6, v5
	v_and_b32_e32 v4, 63, v4
	v_cndmask_b32_e64 v4, v4, v5, s[6:7]
	v_cvt_f32_i32_e32 v4, v4
	v_mul_f32_e32 v4, v6, v4
	v_mul_f32_e32 v4, 0.15915494, v4
	v_sin_f32_e32 v5, v4
	v_cos_f32_e32 v4, v4
	s_waitcnt vmcnt(0) lgkmcnt(0)
	v_lshlrev_b32_e32 v3, 16, v3
	v_mul_f32_e32 v3, v5, v3
	v_cndmask_b32_e64 v3, v3, -v3, s[4:5]
	v_fmac_f32_e32 v3, v4, v7
	v_mov_b32_e32 v7, v3
.LBB0_1367:
	v_ashrrev_i32_e32 v71, 31, v70
	v_bfe_u32 v3, v7, 16, 1
	v_lshlrev_b64 v[4:5], 6, v[70:71]
	v_add3_u32 v3, v7, v3, s60
	v_lshl_add_u64 v[4:5], v[0:1], 0, v[4:5]
	global_store_short_d16_hi v[4:5], v3, off
	v_add_u32_e32 v3, 0x300, v79
	v_ashrrev_i32_e32 v84, 5, v3
	v_add_u32_e32 v72, s27, v84
	v_mov_b64_e32 v[4:5], s[10:11]
	v_mad_i64_i32 v[4:5], s[10:11], v72, s34, v[4:5]
	v_lshl_add_u64 v[4:5], v[4:5], 0, s[20:21]
	v_lshl_add_u64 v[8:9], v[4:5], 0, v[64:65]
	v_mov_b32_e32 v3, v234
	s_and_b64 vcc, exec, s[0:1]
	s_waitcnt vmcnt(0) lgkmcnt(0)
	v_lshlrev_b32_e32 v7, 16, v3
	s_cbranch_vccnz .LBB0_1369
	v_mov_b32_e32 v3, v65
	v_lshl_add_u64 v[2:3], v[4:5], 0, v[2:3]
	v_mov_b32_e32 v2, v238
	v_add_u32_e32 v3, s12, v84
	v_add_u32_e32 v4, 0xffffff00, v3
	v_ashrrev_i32_e32 v4, 6, v4
	v_and_b32_e32 v3, 63, v3
	v_cndmask_b32_e64 v3, v3, v4, s[6:7]
	v_cvt_f32_i32_e32 v3, v3
	v_mul_f32_e32 v3, v6, v3
	v_mul_f32_e32 v3, 0.15915494, v3
	v_sin_f32_e32 v4, v3
	v_cos_f32_e32 v3, v3
	s_waitcnt vmcnt(0) lgkmcnt(0)
	v_lshlrev_b32_e32 v2, 16, v2
	v_mul_f32_e32 v2, v4, v2
	v_cndmask_b32_e64 v2, v2, -v2, s[4:5]
	v_fmac_f32_e32 v2, v3, v7
	v_mov_b32_e32 v7, v2
